# early L2 write-back: every workgroup's barrier thread issues buffer_wbl2 on arrival at grid barriers 1-3
# baseline (speedup 1.0000x reference)
.LBB0_39:
	s_waitcnt vmcnt(0)
	s_barrier
	s_and_saveexec_b64 s[0:1], s[92:93]
	s_cbranch_execz .LBB0_91
	buffer_wbl2 sc1
	s_add_i32 s14, 0, 0x20020
	v_mov_b32_e32 v0, s14
	s_waitcnt vmcnt(0) expcnt(0) lgkmcnt(0)
	ds_read_b32 v2, v0
	s_add_i32 s14, 0, 0x20024
	v_mov_b32_e32 v0, s14
	ds_read_b32 v0, v0
	s_waitcnt lgkmcnt(1)
	v_cmp_ne_u32_e32 vcc, 0, v2
	s_cbranch_vccnz .LBB0_55
	s_add_u32 s14, s52, 0x1200
	s_addc_u32 s15, s53, 0
	s_add_u32 s16, s52, 0x1400
	s_addc_u32 s17, s53, 0
	s_add_u32 s28, s52, 0x1500
	s_addc_u32 s29, s53, 0
	s_add_u32 s46, s52, 0x1600
	s_addc_u32 s47, s53, 0
	s_add_u32 s48, s52, 0x1700
	s_addc_u32 s49, s53, 0
	s_add_u32 s50, s52, 0x1800
	s_addc_u32 s51, s53, 0
	s_add_u32 s56, s52, 0x1900
	s_addc_u32 s57, s53, 0
	s_add_u32 s58, s52, 0x1a00
	s_addc_u32 s59, s53, 0
	s_add_u32 s60, s52, 0x1b00
	s_addc_u32 s61, s53, 0
	s_add_u32 s62, s52, 0x1c00
	s_addc_u32 s63, s53, 0
	s_add_u32 s64, s52, 0x1d00
	s_addc_u32 s65, s53, 0
	s_add_u32 s66, s52, 0x1e00
	s_addc_u32 s67, s53, 0
	s_add_u32 s68, s52, 0x1f00
	s_addc_u32 s69, s53, 0
	s_add_u32 s70, s52, 0x2000
	s_addc_u32 s71, s53, 0
	s_add_u32 s72, s52, 0x2100
	s_addc_u32 s73, s53, 0
	s_add_u32 s74, s52, 0x2200
	s_addc_u32 s75, s53, 0
	s_mul_i32 s84, s11, s33
	s_add_u32 s76, s52, 0x2300
	s_mul_i32 s84, s84, s10
	s_addc_u32 s77, s53, 0
	s_mov_b32 s85, 1
	v_mov_b32_e32 v16, 0
	s_branch .LBB0_43

.LBB0_191:
	s_waitcnt vmcnt(0)
	s_waitcnt vmcnt(0)
	s_barrier
	s_and_saveexec_b64 s[0:1], s[92:93]
	s_cbranch_execz .LBB0_243
	buffer_wbl2 sc1
	s_add_i32 s4, 0, 0x20020
	v_mov_b32_e32 v0, s4
	s_waitcnt vmcnt(0) expcnt(0) lgkmcnt(0)
	ds_read_b32 v2, v0
	s_add_i32 s4, 0, 0x20024
	v_mov_b32_e32 v0, s4
	ds_read_b32 v0, v0
	s_waitcnt lgkmcnt(1)
	v_cmp_ne_u32_e32 vcc, 0, v2
	s_cbranch_vccnz .LBB0_207
	s_add_u32 s4, s52, 0x1200
	s_addc_u32 s5, s53, 0
	s_add_u32 s6, s52, 0x1400
	s_addc_u32 s7, s53, 0
	s_add_u32 s16, s52, 0x1500
	s_addc_u32 s17, s53, 0
	s_add_u32 s44, s52, 0x1600
	s_addc_u32 s45, s53, 0
	s_add_u32 s46, s52, 0x1700
	s_addc_u32 s47, s53, 0
	s_add_u32 s48, s52, 0x1800
	s_addc_u32 s49, s53, 0
	s_add_u32 s50, s52, 0x1900
	s_addc_u32 s51, s53, 0
	s_add_u32 s56, s52, 0x1a00
	s_addc_u32 s57, s53, 0
	s_add_u32 s58, s52, 0x1b00
	s_addc_u32 s59, s53, 0
	s_add_u32 s60, s52, 0x1c00
	s_addc_u32 s61, s53, 0
	s_add_u32 s62, s52, 0x1d00
	s_addc_u32 s63, s53, 0
	s_add_u32 s64, s52, 0x1e00
	s_addc_u32 s65, s53, 0
	s_add_u32 s66, s52, 0x1f00
	s_addc_u32 s67, s53, 0
	s_add_u32 s68, s52, 0x2000
	s_addc_u32 s69, s53, 0
	s_add_u32 s70, s52, 0x2100
	s_addc_u32 s71, s53, 0
	s_add_u32 s72, s52, 0x2200
	s_addc_u32 s73, s53, 0
	s_mul_i32 s82, s11, s33
	s_add_u32 s74, s52, 0x2300
	s_mul_i32 s82, s82, s10
	s_addc_u32 s75, s53, 0
	s_mov_b32 s83, 1
	v_mov_b32_e32 v16, 0
	s_branch .LBB0_195

.Lxa_skip:
	s_and_saveexec_b64 s[0:1], s[92:93]
	s_cbranch_execz .LBB0_363
	buffer_wbl2 sc1
	s_add_i32 s4, 0, 0x20020
	v_mov_b32_e32 v0, s4
	s_waitcnt vmcnt(0) expcnt(0) lgkmcnt(0)
	ds_read_b32 v2, v0
	s_add_i32 s4, 0, 0x20024
	v_mov_b32_e32 v0, s4
	ds_read_b32 v0, v0
	s_waitcnt lgkmcnt(1)
	v_cmp_ne_u32_e32 vcc, 0, v2
	s_cbranch_vccnz .LBB0_327
	s_add_u32 s4, s52, 0x1200
	s_addc_u32 s5, s53, 0
	s_add_u32 s6, s52, 0x1400
	s_addc_u32 s7, s53, 0
	s_add_u32 s20, s52, 0x1500
	s_addc_u32 s21, s53, 0
	s_add_u32 s22, s52, 0x1600
	s_addc_u32 s23, s53, 0
	s_add_u32 s24, s52, 0x1700
	s_addc_u32 s25, s53, 0
	s_add_u32 s26, s52, 0x1800
	s_addc_u32 s27, s53, 0
	s_add_u32 s36, s52, 0x1900
	s_addc_u32 s37, s53, 0
	s_add_u32 s38, s52, 0x1a00
	s_addc_u32 s39, s53, 0
	s_add_u32 s40, s52, 0x1b00
	s_addc_u32 s41, s53, 0
	s_add_u32 s44, s52, 0x1c00
	s_addc_u32 s45, s53, 0
	s_add_u32 s46, s52, 0x1d00
	s_addc_u32 s47, s53, 0
	s_add_u32 s48, s52, 0x1e00
	s_addc_u32 s49, s53, 0
	s_add_u32 s50, s52, 0x1f00
	s_addc_u32 s51, s53, 0
	s_add_u32 s56, s52, 0x2000
	s_addc_u32 s57, s53, 0
	s_add_u32 s58, s52, 0x2100
	s_addc_u32 s59, s53, 0
	s_add_u32 s60, s52, 0x2200
	s_addc_u32 s61, s53, 0
	s_mul_i32 s70, s11, s33
	s_add_u32 s62, s52, 0x2300
	s_mul_i32 s70, s70, s10
	s_addc_u32 s63, s53, 0
	s_mov_b32 s71, 1
	v_mov_b32_e32 v16, 0
	s_branch .LBB0_315
